# P0 rmsnorm(x) row loop: attn_norm gain quads loaded once before the loop instead of one per store behind vmcnt(0) (on top of the contiguous-mapping P9 loop)
# speedup vs baseline: 1.0126x; 1.0057x over previous
; __device__ void phase0(const Params& p, LAS unsigned char* lds, const int WID) {
;     ...
;     { const float* x = p.in[0]; const float* gm = p.in[2]; bf16_t* xa = (bf16_t*)(ws + WS_XA);
;       for (int r = bx * 8 + wid; r < MTOK; r += G * 8) { const float* xr = x + (size_t)r * DM; f32x4 v[8]; float s = 0.f;
; #pragma unroll
;           for (int i = 0; i < 8; ++i) { v[i] = __builtin_nontemporal_load((const f32x4*)(xr + i * 256 + lane * 4)); s += (v[i][0] * v[i][0] + v[i][1] * v[i][1]) + (v[i][2] * v[i][2] + v[i][3] * v[i][3]); }
.LBB0_4:
	s_or_b64 exec, exec, s[6:7]
	s_load_dwordx16 s[56:71], s[0:1], 0x0
	s_load_dwordx16 s[72:87], s[0:1], 0x40
	s_lshr_b32 s1, s40, 6
	s_lshl_b32 s0, s2, 3
	s_add_i32 s14, s1, s0
	s_cmpk_lt_i32 s14, 0x4000
	v_writelane_b32 v254, s1, 0
	s_cselect_b64 s[0:1], -1, 0
	v_writelane_b32 v254, s0, 1
	s_lshl_b32 s16, s96, 3
	v_mbcnt_lo_u32_b32 v42, -1, 0
	v_mbcnt_hi_u32_b32 v42, -1, v42
	s_and_b64 vcc, exec, s[0:1]
	v_writelane_b32 v254, s1, 2
	v_lshlrev_b32_e32 v26, 2, v42
	v_mbcnt_lo_u32_b32 v146, -1, 0
	s_cbranch_vccz .LBB0_7
	v_mbcnt_hi_u32_b32 v4, -1, v146
	v_and_b32_e32 v2, 64, v4
	v_add_u32_e32 v5, 64, v2
	v_xor_b32_e32 v6, 32, v4
	v_cmp_lt_i32_e32 vcc, v6, v5
	v_ashrrev_i32_e32 v27, 31, v26
	v_lshlrev_b64 v[2:3], 2, v[26:27]
	v_cndmask_b32_e32 v6, v4, v6, vcc
	v_lshlrev_b32_e32 v43, 2, v6
	v_xor_b32_e32 v6, 16, v4
	v_cmp_lt_i32_e32 vcc, v6, v5
	s_waitcnt lgkmcnt(0)
	v_lshl_add_u64 v[28:29], s[60:61], 0, v[2:3]
	s_mov_b64 s[6:7], 0x1400
	v_cndmask_b32_e32 v6, v4, v6, vcc
	v_lshlrev_b32_e32 v44, 2, v6
	v_xor_b32_e32 v6, 8, v4
	v_cmp_lt_i32_e32 vcc, v6, v5
	v_lshl_add_u64 v[32:33], v[28:29], 0, s[6:7]
	s_mov_b64 s[6:7], 0x1800
	v_cndmask_b32_e32 v6, v4, v6, vcc
	v_lshlrev_b32_e32 v45, 2, v6
	v_xor_b32_e32 v6, 4, v4
	v_lshl_add_u64 v[34:35], v[28:29], 0, s[6:7]
	s_mov_b64 s[6:7], 0x1c00
	s_ashr_i32 s15, s14, 31
	v_cmp_lt_i32_e32 vcc, v6, v5
	v_lshl_add_u64 v[36:37], v[28:29], 0, s[6:7]
	s_lshl_b64 s[6:7], s[14:15], 13
	v_cndmask_b32_e32 v6, v4, v6, vcc
	s_add_u32 s6, s56, s6
	v_lshlrev_b32_e32 v46, 2, v6
	v_xor_b32_e32 v6, 2, v4
	s_addc_u32 s7, s57, s7
	v_cmp_lt_i32_e32 vcc, v6, v5
	s_mov_b64 s[0:1], 0x1000
	v_lshl_add_u64 v[2:3], s[6:7], 0, v[2:3]
	s_ashr_i32 s17, s16, 31
	v_cndmask_b32_e32 v6, v4, v6, vcc
	v_lshl_add_u64 v[30:31], v[28:29], 0, s[0:1]
	v_lshl_add_u64 v[38:39], v[2:3], 0, s[0:1]
	s_lshl_b64 s[0:1], s[16:17], 13
	s_lshl_b64 s[6:7], s[14:15], 12
	v_lshlrev_b32_e32 v47, 2, v6
	v_xor_b32_e32 v6, 1, v4
	s_add_u32 s6, s94, s6
	v_cmp_lt_i32_e32 vcc, v6, v5
	s_addc_u32 s7, s95, s7
	v_lshl_add_u64 v[2:3], v[26:27], 1, s[6:7]
	v_cndmask_b32_e32 v4, v4, v6, vcc
	s_mov_b64 s[6:7], 0x14f00000
	v_lshlrev_b32_e32 v48, 2, v4
	v_lshl_add_u64 v[40:41], v[2:3], 0, s[6:7]
	s_lshl_b64 s[6:7], s[16:17], 12
	v_mov_b32_e32 v27, 0x358637bd
	s_mov_b32 s8, 0x800000
	s_mov_b32 s9, s14
	global_load_dwordx4 v[160:163], v[28:29], off
	global_load_dwordx4 v[164:167], v[28:29], off offset:1024
	global_load_dwordx4 v[168:171], v[28:29], off offset:2048
	global_load_dwordx4 v[172:175], v[28:29], off offset:3072
	global_load_dwordx4 v[176:179], v[30:31], off
	global_load_dwordx4 v[180:183], v[32:33], off
	global_load_dwordx4 v[184:187], v[34:35], off
	global_load_dwordx4 v[188:191], v[36:37], off
; __device__ __forceinline__ unsigned cvt_pk_bf16(float lo, float hi) { unsigned r; asm volatile("v_cvt_pk_bf16_f32 %0, %1, %2" : "=v"(r) : "v"(lo), "v"(hi)); return r; }
; __device__ void phase0(const Params& p, LAS unsigned char* lds, const int WID) {
;     ...
;       for (int r = bx * 8 + wid; r < MTOK; r += G * 8) { const float* xr = x + (size_t)r * DM; f32x4 v[8]; float s = 0.f;
; #pragma unroll
;           for (int i = 0; i < 8; ++i) { v[i] = __builtin_nontemporal_load((const f32x4*)(xr + i * 256 + lane * 4)); s += (v[i][0] * v[i][0] + v[i][1] * v[i][1]) + (v[i][2] * v[i][2] + v[i][3] * v[i][3]); }
; #pragma unroll
;           for (int o = 32; o >= 1; o >>= 1) s += __shfl_xor(s, o);
;           const float rstd = rsqrtf(s * (1.0f / 2048.0f) + EPS);
; #pragma unroll
;           for (int i = 0; i < 8; ++i) { const f32x4 gv = *(const f32x4*)(gm + i * 256 + lane * 4); u32x2 w; w.x = cvt_pk_bf16(v[i][0] * rstd * gv[0], v[i][1] * rstd * gv[1]); w.y = cvt_pk_bf16(v[i][2] * rstd * gv[2], v[i][3] * rstd * gv[3]);
;               *(u32x2*)(xa + (size_t)r * DM + i * 256 + lane * 4) = w; } } }
.LBB0_6:
	global_load_dwordx4 v[50:53], v[38:39], off offset:-4096 nt
	global_load_dwordx4 v[14:17], v[38:39], off offset:-3072 nt
	global_load_dwordx4 v[18:21], v[38:39], off offset:-2048 nt
	global_load_dwordx4 v[6:9], v[38:39], off offset:1024 nt
	global_load_dwordx4 v[22:25], v[38:39], off nt
	global_load_dwordx4 v[54:57], v[38:39], off offset:-1024 nt
	global_load_dwordx4 v[10:13], v[38:39], off offset:2048 nt
	global_load_dwordx4 v[2:5], v[38:39], off offset:3072 nt
	s_add_i32 s9, s9, s16
	v_lshl_add_u64 v[38:39], v[38:39], 0, s[0:1]
	s_cmpk_gt_i32 s9, 0x3fff
	s_waitcnt vmcnt(7)
	v_mov_b32_e32 v64, v51
	s_waitcnt vmcnt(6)
	v_mov_b32_e32 v65, v15
	s_waitcnt vmcnt(5)
	v_pk_mul_f32 v[66:67], v[20:21], v[20:21]
	v_pk_mul_f32 v[68:69], v[18:19], v[18:19]
	s_waitcnt vmcnt(4)
	v_pk_mul_f32 v[70:71], v[8:9], v[8:9]
	v_pk_mul_f32 v[72:73], v[6:7], v[6:7]
	v_mov_b32_e32 v76, v53
	v_mov_b32_e32 v77, v17
	v_mov_b32_e32 v62, v50
	v_mov_b32_e32 v63, v14
	v_mov_b32_e32 v74, v52
	v_mov_b32_e32 v75, v16
	v_pk_mov_b32 v[86:87], v[68:69], v[66:67] op_sel:[1,0]
	v_mov_b32_e32 v69, v67
	v_pk_mov_b32 v[66:67], v[72:73], v[70:71] op_sel:[1,0]
	v_mov_b32_e32 v73, v71
	v_pk_mul_f32 v[64:65], v[64:65], v[64:65]
	v_pk_mul_f32 v[70:71], v[76:77], v[76:77]
	v_pk_fma_f32 v[62:63], v[62:63], v[62:63], v[64:65]
	v_pk_fma_f32 v[64:65], v[74:75], v[74:75], v[70:71]
	s_waitcnt vmcnt(2)
	v_mul_f32_e32 v78, v55, v55
	v_mul_f32_e32 v80, v57, v57
	v_pk_add_f32 v[68:69], v[86:87], v[68:69]
	v_pk_add_f32 v[62:63], v[62:63], v[64:65]
	v_mul_f32_e32 v49, v24, v24
	v_mul_f32_e32 v85, v25, v25
	v_mul_f32_e32 v90, v23, v23
	v_mul_f32_e32 v91, v22, v22
	v_pk_fma_f32 v[76:77], v[54:55], v[54:55], v[78:79] op_sel_hi:[1,1,0]
	v_pk_fma_f32 v[78:79], v[56:57], v[56:57], v[80:81] op_sel_hi:[1,1,0]
	v_pk_add_f32 v[68:69], v[68:69], v[68:69] op_sel:[0,1] op_sel_hi:[1,0]
	v_pk_add_f32 v[62:63], v[62:63], v[62:63] op_sel:[0,1] op_sel_hi:[1,0]
	v_mov_b32_e32 v77, v49
	v_mov_b32_e32 v79, v85
	v_mov_b32_e32 v69, v90
	v_mov_b32_e32 v63, v91
	v_pk_add_f32 v[64:65], v[76:77], v[78:79]
	v_pk_add_f32 v[62:63], v[62:63], v[68:69]
	s_waitcnt vmcnt(1)
	v_mul_f32_e32 v82, v11, v11
	v_mul_f32_e32 v84, v13, v13
	v_pk_add_f32 v[66:67], v[66:67], v[72:73]
	v_pk_add_f32 v[62:63], v[62:63], v[64:65]
	s_waitcnt vmcnt(0)
	v_mul_f32_e32 v88, v4, v4
	v_mul_f32_e32 v89, v5, v5
	v_mul_f32_e32 v92, v3, v3
	v_mul_f32_e32 v93, v2, v2
	v_pk_fma_f32 v[80:81], v[10:11], v[10:11], v[82:83] op_sel_hi:[1,1,0]
	v_pk_fma_f32 v[82:83], v[12:13], v[12:13], v[84:85] op_sel_hi:[1,1,0]
	v_pk_add_f32 v[66:67], v[66:67], v[66:67] op_sel:[0,1] op_sel_hi:[1,0]
	v_pk_add_f32 v[62:63], v[62:63], v[62:63] op_sel:[0,1] op_sel_hi:[1,0]
	v_mov_b32_e32 v81, v88
	v_mov_b32_e32 v83, v89
	v_mov_b32_e32 v67, v92
	v_mov_b32_e32 v63, v93
	v_pk_add_f32 v[70:71], v[80:81], v[82:83]
	v_pk_add_f32 v[62:63], v[62:63], v[66:67]
	s_nop 0
	v_pk_add_f32 v[62:63], v[62:63], v[70:71]
	s_nop 0
	v_add_f32_e32 v49, v62, v63
	ds_bpermute_b32 v62, v43, v49
	s_waitcnt lgkmcnt(0)
	v_add_f32_e32 v49, v49, v62
	ds_bpermute_b32 v62, v44, v49
	s_waitcnt lgkmcnt(0)
	v_add_f32_e32 v49, v49, v62
	ds_bpermute_b32 v62, v45, v49
	s_waitcnt lgkmcnt(0)
	v_add_f32_e32 v49, v49, v62
	ds_bpermute_b32 v62, v46, v49
	s_waitcnt lgkmcnt(0)
	v_add_f32_e32 v49, v49, v62
	ds_bpermute_b32 v62, v47, v49
	s_waitcnt lgkmcnt(0)
	v_add_f32_e32 v49, v49, v62
	ds_bpermute_b32 v62, v48, v49
	s_waitcnt lgkmcnt(0)
	v_add_f32_e32 v49, v49, v62
	v_fmamk_f32 v49, v49, 0x3a000000, v27
	v_mul_f32_e32 v62, 0x4b800000, v49
	v_cmp_gt_f32_e32 vcc, s8, v49
	s_nop 1
	v_cndmask_b32_e32 v49, v49, v62, vcc
	v_rsq_f32_e32 v49, v49
	s_nop 0
	v_mul_f32_e32 v62, 0x45800000, v49
	v_cndmask_b32_e32 v49, v49, v62, vcc
	v_mul_f32_e32 v50, v50, v49
	v_mul_f32_e32 v51, v51, v49
	v_mul_f32_e32 v52, v52, v49
	v_mul_f32_e32 v53, v53, v49
	v_mul_f32_e32 v50, v160, v50
	v_mul_f32_e32 v51, v161, v51
	v_mul_f32_e32 v52, v162, v52
	v_mul_f32_e32 v53, v163, v53
	v_cvt_pk_bf16_f32 v50, v50, v51
	v_cvt_pk_bf16_f32 v51, v52, v53
	global_store_dwordx2 v[40:41], v[50:51], off
	v_mul_f32_e32 v14, v14, v49
	v_mul_f32_e32 v15, v15, v49
	v_mul_f32_e32 v16, v16, v49
	v_mul_f32_e32 v17, v17, v49
	v_mul_f32_e32 v18, v18, v49
	v_mul_f32_e32 v19, v19, v49
	v_mul_f32_e32 v20, v20, v49
	v_mul_f32_e32 v21, v21, v49
	v_mul_f32_e32 v6, v6, v49
	v_mul_f32_e32 v7, v7, v49
	v_mul_f32_e32 v8, v8, v49
	v_mul_f32_e32 v9, v9, v49
	v_mul_f32_e32 v10, v10, v49
	v_mul_f32_e32 v11, v11, v49
	v_mul_f32_e32 v12, v12, v49
	v_mul_f32_e32 v13, v13, v49
	v_mul_f32_e32 v2, v2, v49
	v_mul_f32_e32 v3, v3, v49
	v_mul_f32_e32 v4, v4, v49
	v_mul_f32_e32 v5, v5, v49
	v_mul_f32_e32 v14, v164, v14
	v_mul_f32_e32 v15, v165, v15
	v_mul_f32_e32 v16, v166, v16
	v_mul_f32_e32 v17, v167, v17
	v_cvt_pk_bf16_f32 v14, v14, v15
	v_cvt_pk_bf16_f32 v15, v16, v17
	global_store_dwordx2 v[40:41], v[14:15], off offset:512
	v_mul_f32_e32 v14, v168, v18
	v_mul_f32_e32 v15, v169, v19
	v_mul_f32_e32 v16, v170, v20
	v_mul_f32_e32 v17, v171, v21
	v_cvt_pk_bf16_f32 v14, v14, v15
	v_cvt_pk_bf16_f32 v15, v16, v17
	global_store_dwordx2 v[40:41], v[14:15], off offset:1024
	v_mul_f32_e32 v18, v54, v49
	v_mul_f32_e32 v19, v55, v49
	v_mul_f32_e32 v20, v56, v49
	v_mul_f32_e32 v21, v57, v49
	v_mul_f32_e32 v14, v172, v18
	v_mul_f32_e32 v15, v173, v19
	v_mul_f32_e32 v16, v174, v20
	v_mul_f32_e32 v17, v175, v21
	v_cvt_pk_bf16_f32 v14, v14, v15
	v_cvt_pk_bf16_f32 v15, v16, v17
	global_store_dwordx2 v[40:41], v[14:15], off offset:1536
	v_mul_f32_e32 v18, v22, v49
	v_mul_f32_e32 v19, v23, v49
	v_mul_f32_e32 v20, v24, v49
	v_mul_f32_e32 v21, v25, v49
	v_mul_f32_e32 v14, v18, v176
	v_mul_f32_e32 v15, v19, v177
	v_mul_f32_e32 v16, v20, v178
	v_mul_f32_e32 v17, v21, v179
	v_cvt_pk_bf16_f32 v14, v14, v15
	v_cvt_pk_bf16_f32 v15, v16, v17
	global_store_dwordx2 v[40:41], v[14:15], off offset:2048
	v_mul_f32_e32 v6, v6, v180
	v_mul_f32_e32 v7, v7, v181
	v_mul_f32_e32 v8, v8, v182
	v_mul_f32_e32 v9, v9, v183
	v_cvt_pk_bf16_f32 v6, v6, v7
	v_cvt_pk_bf16_f32 v7, v8, v9
	global_store_dwordx2 v[40:41], v[6:7], off offset:2560
	v_mul_f32_e32 v6, v10, v184
	v_mul_f32_e32 v7, v11, v185
	v_mul_f32_e32 v8, v12, v186
	v_mul_f32_e32 v9, v13, v187
	v_cvt_pk_bf16_f32 v6, v6, v7
	v_cvt_pk_bf16_f32 v7, v8, v9
	global_store_dwordx2 v[40:41], v[6:7], off offset:3072
	v_mul_f32_e32 v2, v2, v188
	v_mul_f32_e32 v3, v3, v189
	v_mul_f32_e32 v4, v4, v190
	v_mul_f32_e32 v5, v5, v191
	v_cvt_pk_bf16_f32 v2, v2, v3
	v_cvt_pk_bf16_f32 v3, v4, v5
	global_store_dwordx2 v[40:41], v[2:3], off offset:3584
	v_lshl_add_u64 v[40:41], v[40:41], 0, s[6:7]
	s_cbranch_scc0 .LBB0_6
